# P8 epilogue residual (x1 bf16) loads without the nt hint: each 128-B line is touched by several 8-byte-per-lane loads, so it should stay in L2 between them
# speedup vs baseline: 1.0078x; 1.0071x over previous
.LBB0_1092:
	v_lshl_or_b32 v128, s47, 8, v166
	v_lshl_add_u32 v160, s46, 8, v164
	s_ashr_i32 s20, s46, 3
	v_ashrrev_i32_e32 v129, 31, v128
	v_ashrrev_i32_e32 v161, 31, v160
	s_mul_hi_i32 s21, s20, 0xc000
	s_mul_i32 s20, s20, 0xc000
	v_lshl_add_u64 v[158:159], v[128:129], 1, s[28:29]
	v_lshlrev_b64 v[130:131], 12, v[160:161]
	s_add_u32 s20, s35, s20
	v_lshl_add_u64 v[130:131], v[158:159], 0, v[130:131]
	v_lshlrev_b64 v[156:157], 2, v[128:129]
	s_addc_u32 s21, s44, s21
	global_load_dwordx2 v[170:171], v[130:131], off
	global_load_dwordx2 v[172:173], v[130:131], off offset:32
	global_load_dwordx2 v[176:177], v[130:131], off offset:288
	v_lshl_add_u64 v[128:129], s[20:21], 0, v[156:157]
	v_or_b32_e32 v178, 16, v160
	global_load_dwordx2 v[174:175], v[130:131], off offset:256
	global_load_dwordx4 v[132:135], v[128:129], off offset:512
	global_load_dwordx4 v[140:143], v[128:129], off
	global_load_dwordx4 v[136:139], v[128:129], off offset:64
	v_ashrrev_i32_e32 v179, 31, v178
	global_load_dwordx4 v[128:131], v[128:129], off offset:576
	v_lshlrev_b64 v[162:163], 12, v[178:179]
	v_lshl_add_u64 v[162:163], v[158:159], 0, v[162:163]
	global_load_dwordx2 v[180:181], v[162:163], off
	global_load_dwordx2 v[182:183], v[162:163], off offset:32
	global_load_dwordx2 v[184:185], v[162:163], off offset:256
	global_load_dwordx2 v[186:187], v[162:163], off offset:288
	v_or_b32_e32 v188, 32, v160
	v_ashrrev_i32_e32 v189, 31, v188
	v_lshlrev_b64 v[162:163], 12, v[188:189]
	v_lshl_add_u64 v[190:191], v[158:159], 0, v[162:163]
	global_load_dwordx2 v[192:193], v[190:191], off
	global_load_dwordx2 v[196:197], v[190:191], off offset:32
	v_or_b32_e32 v162, 48, v160
	v_ashrrev_i32_e32 v163, 31, v162
	v_lshlrev_b64 v[198:199], 12, v[162:163]
	v_lshl_add_u64 v[198:199], v[158:159], 0, v[198:199]
	global_load_dwordx2 v[200:201], v[190:191], off offset:256
	s_nop 0
	global_load_dwordx2 v[190:191], v[190:191], off offset:288
	s_nop 0
	global_load_dwordx2 v[202:203], v[198:199], off
	global_load_dwordx2 v[204:205], v[198:199], off offset:32
	global_load_dwordx2 v[206:207], v[198:199], off offset:256
	s_nop 0
	global_load_dwordx2 v[198:199], v[198:199], off offset:288
	v_lshlrev_b64 v[194:195], 13, v[160:161]
	v_lshl_add_u64 v[194:195], s[6:7], 0, v[194:195]
	v_lshlrev_b64 v[178:179], 13, v[178:179]
	v_lshl_add_u64 v[194:195], v[194:195], 0, v[156:157]
	v_lshl_add_u64 v[178:179], s[6:7], 0, v[178:179]
	v_lshl_add_u64 v[178:179], v[178:179], 0, v[156:157]
	s_and_b64 vcc, exec, s[0:1]
	s_mov_b64 s[0:1], -1
	s_waitcnt vmcnt(0)
	v_lshlrev_b32_e32 v208, 16, v170
	v_and_b32_e32 v209, 0xffff0000, v170
	v_lshlrev_b32_e32 v170, 16, v171
	v_and_b32_e32 v171, 0xffff0000, v171
	v_lshlrev_b32_e32 v210, 16, v172
	v_and_b32_e32 v211, 0xffff0000, v172
	v_lshlrev_b32_e32 v172, 16, v173
	v_and_b32_e32 v173, 0xffff0000, v173
	v_lshlrev_b32_e32 v214, 16, v176
	v_and_b32_e32 v215, 0xffff0000, v176
	v_lshlrev_b32_e32 v176, 16, v177
	v_and_b32_e32 v177, 0xffff0000, v177
	v_lshlrev_b32_e32 v212, 16, v174
	v_and_b32_e32 v213, 0xffff0000, v174
	v_lshlrev_b32_e32 v174, 16, v175
	v_and_b32_e32 v175, 0xffff0000, v175
	v_pk_fma_f32 v[126:127], v[126:127], v[142:143], v[170:171]
	v_pk_fma_f32 v[124:125], v[124:125], v[140:141], v[208:209]
	v_pk_fma_f32 v[122:123], v[122:123], v[138:139], v[172:173]
	v_pk_fma_f32 v[110:111], v[110:111], v[130:131], v[176:177]
	v_pk_fma_f32 v[108:109], v[108:109], v[128:129], v[214:215]
	v_lshlrev_b32_e32 v170, 16, v180
	v_and_b32_e32 v171, 0xffff0000, v180
	v_lshlrev_b32_e32 v172, 16, v181
	v_and_b32_e32 v173, 0xffff0000, v181
	v_pk_fma_f32 v[120:121], v[120:121], v[136:137], v[210:211]
	v_pk_fma_f32 v[114:115], v[114:115], v[134:135], v[174:175]
	v_pk_fma_f32 v[112:113], v[112:113], v[132:133], v[212:213]
	flat_store_dwordx4 v[194:195], v[124:127] sc1
	flat_store_dwordx4 v[194:195], v[120:123] offset:64 sc1
	flat_store_dwordx4 v[194:195], v[112:115] offset:512 sc1
	flat_store_dwordx4 v[194:195], v[108:111] offset:576 sc1
	v_lshlrev_b32_e32 v174, 16, v182
	v_and_b32_e32 v175, 0xffff0000, v182
	v_pk_fma_f32 v[110:111], v[118:119], v[142:143], v[172:173]
	v_pk_fma_f32 v[108:109], v[116:117], v[140:141], v[170:171]
	flat_store_dwordx4 v[178:179], v[108:111] sc1
	v_pk_fma_f32 v[104:105], v[104:105], v[136:137], v[174:175]
	s_nop 0
	v_lshlrev_b32_e32 v108, 16, v183
	v_and_b32_e32 v109, 0xffff0000, v183
	v_pk_fma_f32 v[106:107], v[106:107], v[138:139], v[108:109]
	flat_store_dwordx4 v[178:179], v[104:107] offset:64 sc1
	s_nop 1
	v_lshlrev_b32_e32 v104, 16, v184
	v_and_b32_e32 v105, 0xffff0000, v184
	v_lshlrev_b32_e32 v106, 16, v185
	v_and_b32_e32 v107, 0xffff0000, v185
	v_pk_fma_f32 v[102:103], v[102:103], v[134:135], v[106:107]
	v_pk_fma_f32 v[100:101], v[100:101], v[132:133], v[104:105]
	flat_store_dwordx4 v[178:179], v[100:103] offset:512 sc1
	s_nop 1
	v_lshlrev_b32_e32 v100, 16, v186
	v_and_b32_e32 v101, 0xffff0000, v186
	v_lshlrev_b32_e32 v102, 16, v187
	v_and_b32_e32 v103, 0xffff0000, v187
	v_pk_fma_f32 v[94:95], v[94:95], v[130:131], v[102:103]
	v_pk_fma_f32 v[92:93], v[92:93], v[128:129], v[100:101]
	flat_store_dwordx4 v[178:179], v[92:95] offset:576 sc1
	s_nop 1
	v_lshlrev_b32_e32 v92, 16, v192
	v_and_b32_e32 v93, 0xffff0000, v192
	v_pk_fma_f32 v[92:93], v[96:97], v[140:141], v[92:93]
	v_lshlrev_b64 v[96:97], 13, v[188:189]
	v_lshlrev_b32_e32 v94, 16, v193
	v_and_b32_e32 v95, 0xffff0000, v193
	v_lshl_add_u64 v[96:97], s[6:7], 0, v[96:97]
	v_pk_fma_f32 v[94:95], v[98:99], v[142:143], v[94:95]
	v_lshl_add_u64 v[96:97], v[96:97], 0, v[156:157]
	flat_store_dwordx4 v[96:97], v[92:95] sc1
	v_add_u32_e32 v98, 0xb0, v160
	v_ashrrev_i32_e32 v99, 31, v98
	v_lshlrev_b32_e32 v92, 16, v196
	v_and_b32_e32 v93, 0xffff0000, v196
	v_lshlrev_b32_e32 v94, 16, v197
	v_and_b32_e32 v95, 0xffff0000, v197
	v_pk_fma_f32 v[90:91], v[90:91], v[138:139], v[94:95]
	v_pk_fma_f32 v[88:89], v[88:89], v[136:137], v[92:93]
	flat_store_dwordx4 v[96:97], v[88:91] offset:64 sc1
	s_nop 1
	v_lshlrev_b32_e32 v88, 16, v200
	v_and_b32_e32 v89, 0xffff0000, v200
	v_lshlrev_b32_e32 v90, 16, v201
	v_and_b32_e32 v91, 0xffff0000, v201
	v_pk_fma_f32 v[86:87], v[86:87], v[134:135], v[90:91]
	v_pk_fma_f32 v[84:85], v[84:85], v[132:133], v[88:89]
	flat_store_dwordx4 v[96:97], v[84:87] offset:512 sc1
	v_add_u32_e32 v88, 0xa0, v160
	v_ashrrev_i32_e32 v89, 31, v88
	v_lshlrev_b32_e32 v84, 16, v190
	v_and_b32_e32 v85, 0xffff0000, v190
	v_lshlrev_b32_e32 v86, 16, v191
	v_and_b32_e32 v87, 0xffff0000, v191
	v_pk_fma_f32 v[78:79], v[78:79], v[130:131], v[86:87]
	v_pk_fma_f32 v[76:77], v[76:77], v[128:129], v[84:85]
	flat_store_dwordx4 v[96:97], v[76:79] offset:576 sc1
	s_nop 1
	v_lshlrev_b32_e32 v76, 16, v202
	v_and_b32_e32 v77, 0xffff0000, v202
	v_pk_fma_f32 v[76:77], v[80:81], v[140:141], v[76:77]
	v_lshlrev_b64 v[80:81], 13, v[162:163]
	v_lshlrev_b32_e32 v78, 16, v203
	v_and_b32_e32 v79, 0xffff0000, v203
	v_lshl_add_u64 v[80:81], s[6:7], 0, v[80:81]
	v_pk_fma_f32 v[78:79], v[82:83], v[142:143], v[78:79]
	v_lshl_add_u64 v[80:81], v[80:81], 0, v[156:157]
	flat_store_dwordx4 v[80:81], v[76:79] sc1
	s_nop 1
	v_lshlrev_b32_e32 v76, 16, v204
	v_and_b32_e32 v77, 0xffff0000, v204
	v_lshlrev_b32_e32 v78, 16, v205
	v_and_b32_e32 v79, 0xffff0000, v205
	v_pk_fma_f32 v[74:75], v[74:75], v[138:139], v[78:79]
	v_pk_fma_f32 v[72:73], v[72:73], v[136:137], v[76:77]
	flat_store_dwordx4 v[80:81], v[72:75] offset:64 sc1
	v_add_u32_e32 v78, 0x90, v160
	v_ashrrev_i32_e32 v79, 31, v78
	v_lshlrev_b32_e32 v72, 16, v206
	v_and_b32_e32 v73, 0xffff0000, v206
	v_lshlrev_b32_e32 v74, 16, v207
	v_and_b32_e32 v75, 0xffff0000, v207
	v_pk_fma_f32 v[70:71], v[70:71], v[134:135], v[74:75]
	v_pk_fma_f32 v[68:69], v[68:69], v[132:133], v[72:73]
	flat_store_dwordx4 v[80:81], v[68:71] offset:512 sc1
	s_nop 1
	v_lshlrev_b32_e32 v68, 16, v198
	v_and_b32_e32 v69, 0xffff0000, v198
	v_lshlrev_b32_e32 v70, 16, v199
	v_and_b32_e32 v71, 0xffff0000, v199
	v_pk_fma_f32 v[64:65], v[64:65], v[128:129], v[68:69]
	v_add_u32_e32 v68, 0x80, v160
	v_pk_fma_f32 v[66:67], v[66:67], v[130:131], v[70:71]
	v_ashrrev_i32_e32 v69, 31, v68
	flat_store_dwordx4 v[80:81], v[64:67] offset:576 sc1
	s_nop 1
	v_lshlrev_b64 v[64:65], 12, v[68:69]
	v_lshl_add_u64 v[64:65], v[158:159], 0, v[64:65]
	global_load_dwordx2 v[70:71], v[64:65], off
	global_load_dwordx2 v[72:73], v[64:65], off offset:32
	global_load_dwordx2 v[74:75], v[64:65], off offset:256
	global_load_dwordx2 v[76:77], v[64:65], off offset:288
	v_lshlrev_b64 v[64:65], 12, v[78:79]
	v_lshl_add_u64 v[64:65], v[158:159], 0, v[64:65]
	global_load_dwordx2 v[80:81], v[64:65], off
	global_load_dwordx2 v[82:83], v[64:65], off offset:32
	global_load_dwordx2 v[84:85], v[64:65], off offset:256
	global_load_dwordx2 v[86:87], v[64:65], off offset:288
	v_lshlrev_b64 v[64:65], 12, v[88:89]
	v_lshl_add_u64 v[64:65], v[158:159], 0, v[64:65]
	global_load_dwordx2 v[90:91], v[64:65], off
	global_load_dwordx2 v[92:93], v[64:65], off offset:32
	global_load_dwordx2 v[94:95], v[64:65], off offset:256
	global_load_dwordx2 v[96:97], v[64:65], off offset:288
	v_lshlrev_b64 v[64:65], 12, v[98:99]
	v_lshl_add_u64 v[64:65], v[158:159], 0, v[64:65]
	global_load_dwordx2 v[100:101], v[64:65], off
	global_load_dwordx2 v[102:103], v[64:65], off offset:32
	global_load_dwordx2 v[66:67], v[64:65], off offset:256
	s_nop 0
	global_load_dwordx2 v[64:65], v[64:65], off offset:288
	v_lshlrev_b64 v[68:69], 13, v[68:69]
	v_lshl_add_u64 v[68:69], s[6:7], 0, v[68:69]
	v_lshl_add_u64 v[68:69], v[68:69], 0, v[156:157]
	s_waitcnt vmcnt(0)
	v_lshlrev_b32_e32 v104, 16, v70
	v_and_b32_e32 v105, 0xffff0000, v70
	v_lshlrev_b32_e32 v70, 16, v71
	v_and_b32_e32 v71, 0xffff0000, v71
	v_pk_fma_f32 v[62:63], v[62:63], v[142:143], v[70:71]
	v_pk_fma_f32 v[60:61], v[60:61], v[140:141], v[104:105]
	flat_store_dwordx4 v[68:69], v[60:63] sc1
	s_nop 1
	v_lshlrev_b32_e32 v60, 16, v72
	v_and_b32_e32 v61, 0xffff0000, v72
	v_lshlrev_b32_e32 v62, 16, v73
	v_and_b32_e32 v63, 0xffff0000, v73
	v_pk_fma_f32 v[58:59], v[58:59], v[138:139], v[62:63]
	v_pk_fma_f32 v[56:57], v[56:57], v[136:137], v[60:61]
	flat_store_dwordx4 v[68:69], v[56:59] offset:64 sc1
	s_nop 1
	v_lshlrev_b32_e32 v56, 16, v74
	v_and_b32_e32 v57, 0xffff0000, v74
	v_lshlrev_b32_e32 v58, 16, v75
	v_and_b32_e32 v59, 0xffff0000, v75
	v_pk_fma_f32 v[54:55], v[54:55], v[134:135], v[58:59]
	v_pk_fma_f32 v[52:53], v[52:53], v[132:133], v[56:57]
	flat_store_dwordx4 v[68:69], v[52:55] offset:512 sc1
	s_nop 1
	v_lshlrev_b32_e32 v52, 16, v76
	v_and_b32_e32 v53, 0xffff0000, v76
	v_lshlrev_b32_e32 v54, 16, v77
	v_and_b32_e32 v55, 0xffff0000, v77
	v_pk_fma_f32 v[46:47], v[46:47], v[130:131], v[54:55]
	v_pk_fma_f32 v[44:45], v[44:45], v[128:129], v[52:53]
	flat_store_dwordx4 v[68:69], v[44:47] offset:576 sc1
	s_nop 1
	v_lshlrev_b32_e32 v44, 16, v80
	v_and_b32_e32 v45, 0xffff0000, v80
	v_pk_fma_f32 v[44:45], v[48:49], v[140:141], v[44:45]
	v_lshlrev_b64 v[48:49], 13, v[78:79]
	v_lshlrev_b32_e32 v46, 16, v81
	v_and_b32_e32 v47, 0xffff0000, v81
	v_lshl_add_u64 v[48:49], s[6:7], 0, v[48:49]
	v_pk_fma_f32 v[46:47], v[50:51], v[142:143], v[46:47]
	v_lshl_add_u64 v[48:49], v[48:49], 0, v[156:157]
	flat_store_dwordx4 v[48:49], v[44:47] sc1
	s_nop 1
	v_lshlrev_b32_e32 v44, 16, v82
	v_and_b32_e32 v45, 0xffff0000, v82
	v_lshlrev_b32_e32 v46, 16, v83
	v_and_b32_e32 v47, 0xffff0000, v83
	v_pk_fma_f32 v[42:43], v[42:43], v[138:139], v[46:47]
	v_pk_fma_f32 v[40:41], v[40:41], v[136:137], v[44:45]
	flat_store_dwordx4 v[48:49], v[40:43] offset:64 sc1
	s_nop 1
	v_lshlrev_b32_e32 v40, 16, v84
	v_and_b32_e32 v41, 0xffff0000, v84
	v_lshlrev_b32_e32 v42, 16, v85
	v_and_b32_e32 v43, 0xffff0000, v85
	v_pk_fma_f32 v[38:39], v[38:39], v[134:135], v[42:43]
	v_pk_fma_f32 v[36:37], v[36:37], v[132:133], v[40:41]
	flat_store_dwordx4 v[48:49], v[36:39] offset:512 sc1
	s_nop 1
	v_lshlrev_b32_e32 v36, 16, v86
	v_and_b32_e32 v37, 0xffff0000, v86
	v_lshlrev_b32_e32 v38, 16, v87
	v_and_b32_e32 v39, 0xffff0000, v87
	v_pk_fma_f32 v[30:31], v[30:31], v[130:131], v[38:39]
	v_pk_fma_f32 v[28:29], v[28:29], v[128:129], v[36:37]
	flat_store_dwordx4 v[48:49], v[28:31] offset:576 sc1
	s_nop 1
	v_lshlrev_b32_e32 v28, 16, v90
	v_and_b32_e32 v29, 0xffff0000, v90
	v_pk_fma_f32 v[28:29], v[32:33], v[140:141], v[28:29]
	v_lshlrev_b64 v[32:33], 13, v[88:89]
	v_lshlrev_b32_e32 v30, 16, v91
	v_and_b32_e32 v31, 0xffff0000, v91
	v_lshl_add_u64 v[32:33], s[6:7], 0, v[32:33]
	v_pk_fma_f32 v[30:31], v[34:35], v[142:143], v[30:31]
	v_lshl_add_u64 v[32:33], v[32:33], 0, v[156:157]
	flat_store_dwordx4 v[32:33], v[28:31] sc1
	s_nop 1
	v_lshlrev_b32_e32 v28, 16, v92
	v_and_b32_e32 v29, 0xffff0000, v92
	v_lshlrev_b32_e32 v30, 16, v93
	v_and_b32_e32 v31, 0xffff0000, v93
	v_pk_fma_f32 v[26:27], v[26:27], v[138:139], v[30:31]
	v_pk_fma_f32 v[24:25], v[24:25], v[136:137], v[28:29]
	flat_store_dwordx4 v[32:33], v[24:27] offset:64 sc1
	s_nop 1
	v_lshlrev_b32_e32 v24, 16, v94
	v_and_b32_e32 v25, 0xffff0000, v94
	v_lshlrev_b32_e32 v26, 16, v95
	v_and_b32_e32 v27, 0xffff0000, v95
	v_pk_fma_f32 v[22:23], v[22:23], v[134:135], v[26:27]
	v_pk_fma_f32 v[20:21], v[20:21], v[132:133], v[24:25]
	flat_store_dwordx4 v[32:33], v[20:23] offset:512 sc1
	s_nop 1
	v_lshlrev_b32_e32 v20, 16, v96
	v_and_b32_e32 v21, 0xffff0000, v96
	v_lshlrev_b32_e32 v22, 16, v97
	v_and_b32_e32 v23, 0xffff0000, v97
	v_pk_fma_f32 v[14:15], v[14:15], v[130:131], v[22:23]
	v_pk_fma_f32 v[12:13], v[12:13], v[128:129], v[20:21]
	flat_store_dwordx4 v[32:33], v[12:15] offset:576 sc1
	s_nop 1
	v_lshlrev_b32_e32 v12, 16, v100
	v_and_b32_e32 v13, 0xffff0000, v100
	v_pk_fma_f32 v[12:13], v[16:17], v[140:141], v[12:13]
	v_lshlrev_b64 v[16:17], 13, v[98:99]
	v_lshlrev_b32_e32 v14, 16, v101
	v_and_b32_e32 v15, 0xffff0000, v101
	v_lshl_add_u64 v[16:17], s[6:7], 0, v[16:17]
	v_pk_fma_f32 v[14:15], v[18:19], v[142:143], v[14:15]
	v_lshl_add_u64 v[16:17], v[16:17], 0, v[156:157]
	flat_store_dwordx4 v[16:17], v[12:15] sc1
	s_nop 1
	v_lshlrev_b32_e32 v12, 16, v102
	v_and_b32_e32 v13, 0xffff0000, v102
	v_lshlrev_b32_e32 v14, 16, v103
	v_and_b32_e32 v15, 0xffff0000, v103
	v_pk_fma_f32 v[10:11], v[10:11], v[138:139], v[14:15]
	v_pk_fma_f32 v[8:9], v[8:9], v[136:137], v[12:13]
	flat_store_dwordx4 v[16:17], v[8:11] offset:64 sc1
	s_nop 1
	v_lshlrev_b32_e32 v8, 16, v66
	v_and_b32_e32 v9, 0xffff0000, v66
	v_lshlrev_b32_e32 v10, 16, v67
	v_and_b32_e32 v11, 0xffff0000, v67
	v_pk_fma_f32 v[6:7], v[6:7], v[134:135], v[10:11]
	v_pk_fma_f32 v[4:5], v[4:5], v[132:133], v[8:9]
	flat_store_dwordx4 v[16:17], v[4:7] offset:512 sc1
	s_nop 1
	v_lshlrev_b32_e32 v4, 16, v64
	v_and_b32_e32 v5, 0xffff0000, v64
	v_lshlrev_b32_e32 v6, 16, v65
	v_and_b32_e32 v7, 0xffff0000, v65
	v_pk_fma_f32 v[2:3], v[2:3], v[130:131], v[6:7]
	v_pk_fma_f32 v[0:1], v[0:1], v[128:129], v[4:5]
	flat_store_dwordx4 v[16:17], v[0:3] offset:576 sc1
	s_cbranch_vccnz .LBB0_1077
	s_andn2_b64 vcc, exec, s[12:13]
	s_cbranch_vccnz .LBB0_1076
	s_barrier
	s_branch .LBB0_1076
